# P4 stage: wave 0 issues its decay-factor bpermute early so its latency overlaps the conv work
# baseline (speedup 1.0000x reference)
.Lp4n_stg_A:
	s_cmp_lt_u32 s99, 63
	s_cbranch_scc0 .Lp4n_premid_A
	s_bfe_u32 s45, s42, 0x1000c
	s_cmp_eq_u32 s45, 0
	s_cselect_b64 vcc, -1, 0
	v_cndmask_b32_e32 v106, v162, v161, vcc
	v_cndmask_b32_e32 v107, v164, v163, vcc
	v_cndmask_b32_e32 v108, v166, v165, vcc
	v_cndmask_b32_e32 v109, v168, v167, vcc
	s_waitcnt vmcnt(11)
	ds_write_b128 v169, v[34:37] offset:17408
	s_waitcnt vmcnt(10)
	ds_write_b128 v169, v[38:41] offset:26112
	ds_write_b128 v170, v[26:29]
	ds_write_b128 v170, v[30:33] offset:9216
	s_waitcnt vmcnt(9)
	v_and_b32_e32 v102, v42, v106
	v_and_b32_e32 v103, v43, v107
	v_and_b32_e32 v104, v44, v108
	v_and_b32_e32 v105, v45, v109
	ds_write_b128 v171, v[102:105] offset:17408
	s_waitcnt vmcnt(8)
	s_cmp_lg_u32 s97, 0
	s_cbranch_scc1 .Lp4n_gve_A
	s_and_b64 s[20:21], vcc, exec
	s_cselect_b32 s20, 63, 0
	v_and_or_b32 v211, v195, 64, s20
	v_lshlrev_b32_e32 v211, 2, v211
	ds_bpermute_b32 v210, v211, v176
.Lp4n_gve_A:
	v_and_b32_e32 v102, v46, v106
	v_and_b32_e32 v103, v47, v107
	v_and_b32_e32 v104, v48, v108
	v_and_b32_e32 v105, v49, v109
	s_bfe_u32 s45, s42, 0x60016
	s_cmp_lg_u32 s45, 0
	ds_write_b128 v172, v[102:105] offset:9216
	s_cbranch_scc1 .Lp4n_cwkeep_A
	s_waitcnt vmcnt(4)
	v_mov_b64_e32 v[84:85], v[24:25]
	v_mov_b64_e32 v[88:89], v[20:21]
	v_mov_b64_e32 v[92:93], v[16:17]
	v_mov_b64_e32 v[96:97], v[12:13]
	v_mov_b64_e32 v[82:83], v[22:23]
	v_mov_b64_e32 v[86:87], v[18:19]
	v_mov_b64_e32 v[90:91], v[14:15]
	v_mov_b64_e32 v[94:95], v[10:11]
.Lp4n_cwkeep_A:
	v_lshlrev_b32_e32 v102, 16, v128
	v_and_b32_e32 v103, 0xffff0000, v128
	v_pk_mul_f32 v[102:103], v[94:95], v[102:103]
	v_lshlrev_b32_e32 v104, 16, v129
	v_and_b32_e32 v105, 0xffff0000, v129
	v_pk_mul_f32 v[104:105], v[96:97], v[104:105]
	v_lshlrev_b32_e32 v106, 16, v130
	v_and_b32_e32 v107, 0xffff0000, v130
	v_pk_fma_f32 v[102:103], v[90:91], v[106:107], v[102:103]
	v_lshlrev_b32_e32 v108, 16, v131
	v_and_b32_e32 v109, 0xffff0000, v131
	v_pk_fma_f32 v[104:105], v[92:93], v[108:109], v[104:105]
	v_lshlrev_b32_e32 v106, 16, v132
	v_and_b32_e32 v107, 0xffff0000, v132
	v_pk_fma_f32 v[102:103], v[86:87], v[106:107], v[102:103]
	v_lshlrev_b32_e32 v108, 16, v133
	v_and_b32_e32 v109, 0xffff0000, v133
	v_pk_fma_f32 v[104:105], v[88:89], v[108:109], v[104:105]
	v_lshlrev_b32_e32 v106, 16, v136
	v_and_b32_e32 v107, 0xffff0000, v136
	v_pk_fma_f32 v[102:103], v[82:83], v[106:107], v[102:103]
	v_lshlrev_b32_e32 v108, 16, v137
	v_and_b32_e32 v109, 0xffff0000, v137
	v_pk_fma_f32 v[104:105], v[84:85], v[108:109], v[104:105]
	v_pk_mul_f32 v[106:107], v[102:103], s[100:101] op_sel_hi:[1,0]
	v_pk_mul_f32 v[108:109], v[104:105], s[100:101] op_sel_hi:[1,0]
	v_exp_f32_e32 v106, v106
	v_exp_f32_e32 v107, v107
	v_exp_f32_e32 v108, v108
	v_exp_f32_e32 v109, v109
	v_pk_add_f32 v[106:107], v[106:107], 1.0 op_sel_hi:[1,0]
	v_pk_add_f32 v[108:109], v[108:109], 1.0 op_sel_hi:[1,0]
	v_rcp_f32_e32 v106, v106
	v_rcp_f32_e32 v107, v107
	v_rcp_f32_e32 v108, v108
	v_rcp_f32_e32 v109, v109
	v_pk_mul_f32 v[102:103], v[102:103], v[106:107]
	v_pk_mul_f32 v[104:105], v[104:105], v[108:109]
	s_waitcnt vmcnt(7)
	v_mul_f32_e32 v102, v175, v102
	v_mul_f32_e32 v103, v175, v103
	v_mul_f32_e32 v104, v175, v104
	v_mul_f32_e32 v105, v175, v105
	v_cvt_pk_bf16_f32 v102, v102, s0
	v_cvt_pk_bf16_f32 v103, v103, s0
	v_cvt_pk_bf16_f32 v104, v104, s0
	v_cvt_pk_bf16_f32 v105, v105, s0
	ds_write_b16 v197, v102 offset:26624
	ds_write_b16 v197, v103 offset:26768
	ds_write_b16 v197, v104 offset:26912
	ds_write_b16 v197, v105 offset:27056
	s_and_saveexec_b64 s[8:9], s[4:5]
	s_cbranch_execz .Lp4n_w0done_A
	s_mov_b32 s14, 0x1d900
	v_mul_f32_e32 v103, 0x3fb8aa3b, v176
	v_exp_f32_e32 v103, v103
	v_lshl_add_u32 v105, v0, 2, s14
	s_waitcnt lgkmcnt(0)
	v_sub_f32_e32 v104, v210, v176
	v_mul_f32_e32 v104, 0x3fb8aa3b, v104
	v_exp_f32_e32 v104, v104
	v_mul_f32_e32 v106, v177, v103
	ds_write2st64_b32 v105, v103, v106 offset1:1
	ds_write_b32 v105, v104 offset:512
	s_and_b64 exec, exec, s[6:7]
	s_cbranch_execz .Lp4n_w0done_A
	v_mul_f32_e32 v102, 0x3fb8aa3b, v210
	v_exp_f32_e32 v102, v102
	v_mov_b32_e32 v103, s14
	ds_write_b32 v103, v102 offset:768

.Lp4n_stg_B:
	s_cmp_lt_u32 s99, 63
	s_cbranch_scc0 .Lp4n_premid_B
	s_bfe_u32 s45, s42, 0x1000c
	s_cmp_eq_u32 s45, 0
	s_cselect_b64 vcc, -1, 0
	v_cndmask_b32_e32 v6, v162, v161, vcc
	v_cndmask_b32_e32 v7, v164, v163, vcc
	v_cndmask_b32_e32 v8, v166, v165, vcc
	v_cndmask_b32_e32 v9, v168, v167, vcc
	s_waitcnt vmcnt(11)
	ds_write_b128 v169, v[58:61]
	s_waitcnt vmcnt(10)
	ds_write_b128 v169, v[62:65] offset:8704
	ds_write_b128 v170, v[50:53]
	ds_write_b128 v170, v[54:57] offset:9216
	s_waitcnt vmcnt(9)
	v_and_b32_e32 v2, v66, v6
	v_and_b32_e32 v3, v67, v7
	v_and_b32_e32 v4, v68, v8
	v_and_b32_e32 v5, v69, v9
	ds_write_b128 v171, v[2:5] offset:17408
	s_waitcnt vmcnt(8)
	s_cmp_lg_u32 s97, 0
	s_cbranch_scc1 .Lp4n_gve_B
	s_and_b64 s[20:21], vcc, exec
	s_cselect_b32 s20, 63, 0
	v_and_or_b32 v211, v195, 64, s20
	v_lshlrev_b32_e32 v211, 2, v211
	ds_bpermute_b32 v210, v211, v184
.Lp4n_gve_B:
	v_and_b32_e32 v2, v70, v6
	v_and_b32_e32 v3, v71, v7
	v_and_b32_e32 v4, v72, v8
	v_and_b32_e32 v5, v73, v9
	s_bfe_u32 s45, s42, 0x60016
	s_cmp_lg_u32 s45, 0
	ds_write_b128 v172, v[2:5]
	s_cbranch_scc1 .Lp4n_cwkeep_B
	s_waitcnt vmcnt(4)
	v_mov_b64_e32 v[84:85], v[24:25]
	v_mov_b64_e32 v[88:89], v[20:21]
	v_mov_b64_e32 v[92:93], v[16:17]
	v_mov_b64_e32 v[96:97], v[12:13]
	v_mov_b64_e32 v[82:83], v[22:23]
	v_mov_b64_e32 v[86:87], v[18:19]
	v_mov_b64_e32 v[90:91], v[14:15]
	v_mov_b64_e32 v[94:95], v[10:11]
.Lp4n_cwkeep_B:
	v_lshlrev_b32_e32 v2, 16, v134
	v_and_b32_e32 v3, 0xffff0000, v134
	v_pk_mul_f32 v[2:3], v[94:95], v[2:3]
	v_lshlrev_b32_e32 v4, 16, v135
	v_and_b32_e32 v5, 0xffff0000, v135
	v_pk_mul_f32 v[4:5], v[96:97], v[4:5]
	v_lshlrev_b32_e32 v6, 16, v138
	v_and_b32_e32 v7, 0xffff0000, v138
	v_pk_fma_f32 v[2:3], v[90:91], v[6:7], v[2:3]
	v_lshlrev_b32_e32 v8, 16, v139
	v_and_b32_e32 v9, 0xffff0000, v139
	v_pk_fma_f32 v[4:5], v[92:93], v[8:9], v[4:5]
	v_lshlrev_b32_e32 v6, 16, v140
	v_and_b32_e32 v7, 0xffff0000, v140
	v_pk_fma_f32 v[2:3], v[86:87], v[6:7], v[2:3]
	v_lshlrev_b32_e32 v8, 16, v141
	v_and_b32_e32 v9, 0xffff0000, v141
	v_pk_fma_f32 v[4:5], v[88:89], v[8:9], v[4:5]
	v_lshlrev_b32_e32 v6, 16, v142
	v_and_b32_e32 v7, 0xffff0000, v142
	v_pk_fma_f32 v[2:3], v[82:83], v[6:7], v[2:3]
	v_lshlrev_b32_e32 v8, 16, v143
	v_and_b32_e32 v9, 0xffff0000, v143
	v_pk_fma_f32 v[4:5], v[84:85], v[8:9], v[4:5]
	v_pk_mul_f32 v[6:7], v[2:3], s[100:101] op_sel_hi:[1,0]
	v_pk_mul_f32 v[8:9], v[4:5], s[100:101] op_sel_hi:[1,0]
	v_exp_f32_e32 v6, v6
	v_exp_f32_e32 v7, v7
	v_exp_f32_e32 v8, v8
	v_exp_f32_e32 v9, v9
	v_pk_add_f32 v[6:7], v[6:7], 1.0 op_sel_hi:[1,0]
	v_pk_add_f32 v[8:9], v[8:9], 1.0 op_sel_hi:[1,0]
	v_rcp_f32_e32 v6, v6
	v_rcp_f32_e32 v7, v7
	v_rcp_f32_e32 v8, v8
	v_rcp_f32_e32 v9, v9
	v_pk_mul_f32 v[2:3], v[2:3], v[6:7]
	v_pk_mul_f32 v[4:5], v[4:5], v[8:9]
	s_waitcnt vmcnt(7)
	v_mul_f32_e32 v2, v181, v2
	v_mul_f32_e32 v3, v181, v3
	v_mul_f32_e32 v4, v181, v4
	v_mul_f32_e32 v5, v181, v5
	v_cvt_pk_bf16_f32 v2, v2, s0
	v_cvt_pk_bf16_f32 v3, v3, s0
	v_cvt_pk_bf16_f32 v4, v4, s0
	v_cvt_pk_bf16_f32 v5, v5, s0
	ds_write_b16 v197, v2 offset:26624
	ds_write_b16 v197, v3 offset:26768
	ds_write_b16 v197, v4 offset:26912
	ds_write_b16 v197, v5 offset:27056
	s_and_saveexec_b64 s[8:9], s[4:5]
	s_cbranch_execz .Lp4n_w0done_B
	s_mov_b32 s14, 0x1d400
	v_mul_f32_e32 v3, 0x3fb8aa3b, v184
	v_exp_f32_e32 v3, v3
	v_lshl_add_u32 v5, v0, 2, s14
	s_waitcnt lgkmcnt(0)
	v_sub_f32_e32 v4, v210, v184
	v_mul_f32_e32 v4, 0x3fb8aa3b, v4
	v_exp_f32_e32 v4, v4
	v_mul_f32_e32 v6, v185, v3
	ds_write2st64_b32 v5, v3, v6 offset1:1
	ds_write_b32 v5, v4 offset:512
	s_and_b64 exec, exec, s[6:7]
	s_cbranch_execz .Lp4n_w0done_B
	v_mul_f32_e32 v2, 0x3fb8aa3b, v210
	v_exp_f32_e32 v2, v2
	v_mov_b32_e32 v3, s14
	ds_write_b32 v3, v2 offset:768
